# stack: cumsum units all in chunk 0 + LRU pass-1 next-unit L2 touch + LRU conv fma on top of v111
# speedup vs baseline: 1.0122x; 1.0119x over previous
; #define GAS __attribute__((address_space(1)))
; #define LAS __attribute__((address_space(3)))
; template <int PASS>
; __device__ __forceinline__ void lru_unit(const LruPtrs& args, LAS unsigned char* lds, int chunk, int bl, int g, int ck) {
;     ...
;         { const float* src = (w < 4) ? args.conv_w + w * D : (w == 4) ? args.conv_b : (w == 5) ? args.b_lru_r : (w == 6) ? args.b_lru_i : (const float*)(ws + WS_COEF);
;           PRM[w * 64 + lane] = ((const GAS float*)src)[g * 64 + lane]; }
;         LAS bf16* XT = (LAS bf16*)(lds + RING_OFF + 32768 + w * 4864);
;         {
;             const int tl0 = ck * 256 + w * 32;
;             v4u xv[5];
; #pragma unroll
;             for (int i = 0; i < 5; ++i) { const int idx = lane + 64 * i, r = idx >> 3, ch = idx & 7; const int ts = tl0 - 3 + r;
;                 xv[i] = (v4u){0u, 0u, 0u, 0u};
;                 if (r < 35 && ts >= 0) xv[i] = *(const GAS v4u*)(Z + ((size_t)bl * T + ts) * LDZ + ZC_AX + g * 64 + ch * 8); }
; #pragma unroll
;             for (int i = 0; i < 5; ++i) { const int idx = lane + 64 * i, r = idx >> 3, ch = idx & 7;
;                 if (r < 35) { *(LAS v2u*)(XT + r * 68 + ch * 8) = (v2u){xv[i].x, xv[i].y}; *(LAS v2u*)(XT + r * 68 + ch * 8 + 4) = (v2u){xv[i].z, xv[i].w}; } }
;         }
;         __syncthreads();
;         v2u xw[4][8];
; #pragma unroll
;         for (int k = 0; k < 4; ++k)
; #pragma unroll
;             for (int q = 0; q < 8; ++q) xw[k][q] = *(const LAS v2u*)(XT + (n + k) * 68 + 8 * q + 4 * hi);
;         float xc[8][4];
; #pragma unroll
;         for (int q = 0; q < 8; ++q) { const f32x4 bb = *(const LAS f32x4*)(PRM + 4 * 64 + 8 * q + 4 * hi);
; #pragma unroll
;             for (int p = 0; p < 4; ++p) xc[q][p] = bb[p]; }
; #pragma unroll
;         for (int k = 0; k < 4; ++k) {
; #pragma unroll
;             for (int q = 0; q < 8; ++q) { const f32x4 cw = *(const LAS f32x4*)(PRM + k * 64 + 8 * q + 4 * hi);
;                 xc[q][0] += cw[0] * pg8::bf_lo(xw[k][q].x); xc[q][1] += cw[1] * pg8::bf_hi(xw[k][q].x); xc[q][2] += cw[2] * pg8::bf_lo(xw[k][q].y); xc[q][3] += cw[3] * pg8::bf_hi(xw[k][q].y); }
;         }
.LBB0_443:
	s_or_b64 exec, exec, s[4:5]
	s_mul_i32 s4, s48, 0x1300
	s_add_i32 s50, s4, 0
	v_lshl_add_u32 v0, v26, 1, s50
	s_movk_i32 s4, 0x88
	v_mad_u32_u24 v22, v25, s4, v0
	v_add_u32_e32 v23, 0x8000, v22
	s_waitcnt vmcnt(0)
	s_and_saveexec_b64 s[4:5], s[10:11]
	v_mov_b32_e32 v180, s86
	ds_write_b32 v180, v252 offset:64
	s_or_b64 exec, exec, s[4:5]
	ds_write_b32 v179, v178 offset:12288
	ds_write2_b64 v23, v[6:7], v[8:9] offset1:1
	v_add_u32_e32 v6, 0x8440, v22
	ds_write2_b64 v6, v[2:3], v[4:5] offset1:1
	v_add_u32_e32 v2, 0x8880, v22
	ds_write2_b64 v2, v[14:15], v[16:17] offset1:1
	v_add_u32_e32 v2, 0x8cc0, v22
	ds_write2_b64 v2, v[10:11], v[12:13] offset1:1
	s_and_saveexec_b64 s[4:5], vcc
	v_mul_u32_u24_e32 v2, 0x88, v27
	v_add3_u32 v0, v0, v2, s79
	ds_write2_b64 v0, v[18:19], v[20:21] offset1:1
	s_or_b64 exec, exec, s[4:5]
	v_lshrrev_b32_e32 v2, 3, v24
	v_and_b32_e32 v87, 31, v24
	v_and_b32_e32 v88, 4, v2
	v_lshlrev_b32_e32 v2, 1, v88
	v_mul_u32_u24_e32 v3, 0x88, v87
	v_add3_u32 v2, s50, v2, v3
	v_add_u32_e32 v10, 0x8000, v2
	v_lshl_add_u32 v89, v88, 2, 0
	s_waitcnt lgkmcnt(0)
	s_barrier
	ds_read2_b64 v[90:93], v10 offset1:2
	ds_read2_b64 v[82:85], v10 offset0:4 offset1:6
	ds_read2_b64 v[50:53], v10 offset0:8 offset1:10
	ds_read2_b64 v[2:5], v10 offset0:12 offset1:14
	ds_read2_b64 v[94:97], v10 offset0:17 offset1:19
	ds_read2_b64 v[98:101], v10 offset0:21 offset1:23
	ds_read2_b64 v[54:57], v10 offset0:25 offset1:27
	ds_read2_b64 v[6:9], v10 offset0:29 offset1:31
	ds_read2_b64 v[34:37], v10 offset0:34 offset1:36
	ds_read2_b64 v[26:29], v10 offset0:38 offset1:40
	ds_read2_b64 v[18:21], v10 offset0:42 offset1:44
	ds_read2_b64 v[66:69], v10 offset0:46 offset1:48
	ds_read2_b64 v[38:41], v10 offset0:51 offset1:53
	ds_read2_b64 v[30:33], v10 offset0:55 offset1:57
	ds_read2_b64 v[22:25], v10 offset0:59 offset1:61
	ds_read2_b64 v[70:73], v10 offset0:63 offset1:65
	ds_read_b128 v[102:105], v89 offset:13312
	ds_read_b128 v[106:109], v89 offset:13344
	ds_read_b128 v[110:113], v89 offset:13376
	ds_read_b128 v[114:117], v89 offset:13408
	ds_read_b128 v[74:77], v89 offset:13440
	ds_read_b128 v[58:61], v89 offset:13472
	ds_read_b128 v[42:45], v89 offset:13504
	ds_read_b128 v[10:13], v89 offset:13536
	ds_read_b128 v[118:121], v89 offset:12288
	ds_read_b128 v[122:125], v89 offset:12320
	ds_read_b128 v[126:129], v89 offset:12352
	ds_read_b128 v[130:133], v89 offset:12384
	ds_read_b128 v[78:81], v89 offset:12416
	ds_read_b128 v[62:65], v89 offset:12448
	ds_read_b128 v[46:49], v89 offset:12480
	ds_read_b128 v[14:17], v89 offset:12512
	ds_read_b128 v[134:137], v89 offset:12544
	s_waitcnt lgkmcnt(14)
	v_lshlrev_b32_e32 v143, 16, v94
	v_lshlrev_b32_e32 v142, 16, v90
	s_waitcnt lgkmcnt(8)
	ds_read_b128 v[138:141], v89 offset:12576
	s_waitcnt lgkmcnt(1)
	v_fma_f32 v102, v118, v142, v102
	v_fma_f32 v144, v134, v143, v102
	v_and_b32_e32 v143, 0xffff0000, v94
	v_and_b32_e32 v142, 0xffff0000, v90
	v_fma_f32 v90, v119, v142, v103
	v_fma_f32 v134, v135, v143, v90
	v_lshlrev_b32_e32 v102, 16, v91
	v_lshlrev_b32_e32 v103, 16, v95
	v_fma_f32 v90, v120, v102, v104
	v_fma_f32 v135, v136, v103, v90
	v_and_b32_e32 v95, 0xffff0000, v95
	v_and_b32_e32 v94, 0xffff0000, v91
	v_fma_f32 v90, v121, v94, v105
	v_fma_f32 v136, v137, v95, v90
	v_lshlrev_b32_e32 v91, 16, v96
	v_lshlrev_b32_e32 v90, 16, v92
	s_waitcnt lgkmcnt(0)
	v_fma_f32 v90, v122, v90, v106
	v_fma_f32 v122, v138, v91, v90
	v_and_b32_e32 v91, 0xffff0000, v96
	v_and_b32_e32 v90, 0xffff0000, v92
	v_fma_f32 v90, v123, v90, v107
	v_fma_f32 v123, v139, v91, v90
	v_mov_b32_e32 v94, v124
	v_lshlrev_b32_e32 v91, 16, v97
	v_lshlrev_b32_e32 v90, 16, v93
	v_mov_b32_e32 v95, v140
	v_pk_mul_f32 v[90:91], v[94:95], v[90:91]
	v_add_f32_e32 v90, v108, v90
	v_add_f32_e32 v108, v90, v91
	v_and_b32_e32 v91, 0xffff0000, v97
	v_and_b32_e32 v90, 0xffff0000, v93
	v_fma_f32 v90, v125, v90, v109
	v_fma_f32 v124, v141, v91, v90
	v_lshlrev_b32_e32 v103, 16, v98
	ds_read_b128 v[90:93], v89 offset:12608
	ds_read_b128 v[94:97], v89 offset:12640
	v_lshlrev_b32_e32 v102, 16, v82
	s_and_b32 s4, s49, 0x1ffffe00
	s_waitcnt lgkmcnt(1)
	v_mov_b32_e32 v105, v90
	v_fma_f32 v90, v126, v102, v110
	v_fma_f32 v125, v105, v103, v90
	s_lshl_b32 s5, s2, 5
	v_and_b32_e32 v103, 0xffff0000, v98
	v_and_b32_e32 v102, 0xffff0000, v82
	v_mov_b32_e32 v90, v127
	v_fma_f32 v82, v90, v102, v111
	v_fma_f32 v126, v91, v103, v82
	v_lshlrev_b32_e32 v91, 16, v99
	v_lshlrev_b32_e32 v90, 16, v83
	v_fma_f32 v82, v128, v90, v112
	v_fma_f32 v127, v92, v91, v82
	v_and_b32_e32 v91, 0xffff0000, v99
	v_and_b32_e32 v90, 0xffff0000, v83
	v_fma_f32 v82, v129, v90, v113
	v_fma_f32 v128, v93, v91, v82
	v_lshlrev_b32_e32 v83, 16, v100
	v_lshlrev_b32_e32 v82, 16, v84
	s_waitcnt lgkmcnt(0)
	v_fma_f32 v82, v130, v82, v114
	v_fma_f32 v129, v94, v83, v82
	v_and_b32_e32 v83, 0xffff0000, v100
	v_and_b32_e32 v82, 0xffff0000, v84
	v_fma_f32 v82, v131, v82, v115
	v_fma_f32 v130, v95, v83, v82
	v_lshlrev_b32_e32 v83, 16, v101
	v_lshlrev_b32_e32 v82, 16, v85
	v_fma_f32 v82, v132, v82, v116
	v_fma_f32 v131, v96, v83, v82
	v_mov_b32_e32 v96, v133
	v_and_b32_e32 v83, 0xffff0000, v101
	v_and_b32_e32 v82, 0xffff0000, v85
	v_pk_mul_f32 v[82:83], v[96:97], v[82:83]
	v_lshlrev_b32_e32 v91, 16, v54
	v_add_f32_e32 v82, v117, v82
	v_add_f32_e32 v117, v82, v83
	ds_read_b128 v[82:85], v89 offset:12672
	ds_read_b128 v[94:97], v89 offset:12704
	v_lshlrev_b32_e32 v90, 16, v50
	s_or_b32 s4, s5, s4
	s_waitcnt lgkmcnt(1)
; #define LAS __attribute__((address_space(3)))
; template <int PASS>
; __device__ __forceinline__ void lru_unit(const LruPtrs& args, LAS unsigned char* lds, int chunk, int bl, int g, int ck) {
;     ...
;         for (int k = 0; k < 4; ++k) {
; #pragma unroll
;             for (int q = 0; q < 8; ++q) { const f32x4 cw = *(const LAS f32x4*)(PRM + k * 64 + 8 * q + 4 * hi);
;                 xc[q][0] += cw[0] * pg8::bf_lo(xw[k][q].x); xc[q][1] += cw[1] * pg8::bf_hi(xw[k][q].x); xc[q][2] += cw[2] * pg8::bf_lo(xw[k][q].y); xc[q][3] += cw[3] * pg8::bf_hi(xw[k][q].y); }
;         }
	v_fma_f32 v74, v78, v90, v74
	v_fma_f32 v132, v82, v91, v74
	v_and_b32_e32 v91, 0xffff0000, v54
	v_and_b32_e32 v90, 0xffff0000, v50
	v_fma_f32 v50, v79, v90, v75
	v_fma_f32 v133, v83, v91, v50
	v_lshlrev_b32_e32 v74, 16, v51
	v_lshlrev_b32_e32 v75, 16, v55
	v_fma_f32 v50, v80, v74, v76
	v_fma_f32 v92, v84, v75, v50
	v_and_b32_e32 v55, 0xffff0000, v55
	v_and_b32_e32 v54, 0xffff0000, v51
	v_fma_f32 v50, v81, v54, v77
	v_fma_f32 v54, v85, v55, v50
	v_lshlrev_b32_e32 v51, 16, v56
	v_lshlrev_b32_e32 v50, 16, v52
	s_waitcnt lgkmcnt(0)
	v_fma_f32 v50, v62, v50, v58
	v_fma_f32 v51, v94, v51, v50
	v_and_b32_e32 v75, 0xffff0000, v56
	v_and_b32_e32 v74, 0xffff0000, v52
	v_fma_f32 v50, v63, v74, v59
	v_fma_f32 v52, v95, v75, v50
	v_lshlrev_b32_e32 v59, 16, v57
	v_lshlrev_b32_e32 v58, 16, v53
	v_mov_b32_e32 v63, v96
	v_and_b32_e32 v57, 0xffff0000, v57
	v_and_b32_e32 v56, 0xffff0000, v53
	v_fma_f32 v50, v64, v58, v60
	v_fma_f32 v50, v63, v59, v50
	v_fma_f32 v53, v65, v56, v61
	v_fma_f32 v53, v97, v57, v53
	ds_read_b128 v[56:59], v89 offset:12736
	ds_read_b128 v[74:77], v89 offset:12768
	v_lshlrev_b32_e32 v61, 16, v6
	v_lshlrev_b32_e32 v60, 16, v2
	s_waitcnt lgkmcnt(1)
	v_fma_f32 v42, v46, v60, v42
	v_fma_f32 v94, v56, v61, v42
	v_and_b32_e32 v61, 0xffff0000, v6
	v_and_b32_e32 v60, 0xffff0000, v2
	v_fma_f32 v2, v47, v60, v43
	v_fma_f32 v93, v57, v61, v2
	v_lshlrev_b32_e32 v42, 16, v3
	v_lshlrev_b32_e32 v43, 16, v7
	v_fma_f32 v2, v48, v42, v44
	v_fma_f32 v116, v58, v43, v2
	v_and_b32_e32 v7, 0xffff0000, v7
	v_and_b32_e32 v6, 0xffff0000, v3
	v_mov_b32_e32 v58, v49
	v_pk_mul_f32 v[2:3], v[58:59], v[6:7]
	v_lshlrev_b32_e32 v7, 16, v38
	v_add_f32_e32 v2, v45, v2
	ds_read_b128 v[56:59], v89 offset:12800
	ds_read_b128 v[60:63], v89 offset:12832
	ds_read_b128 v[96:99], v89 offset:12864
	ds_read_b128 v[118:121], v89 offset:12896
	ds_read_b128 v[46:49], v89 offset:12928
	ds_read_b128 v[42:45], v89 offset:12960
	ds_read_b128 v[82:85], v89 offset:12992
	ds_read_b128 v[78:81], v89 offset:13024
	ds_read_b128 v[100:103], v89 offset:13056
	v_lshlrev_b32_e32 v6, 16, v34
	s_waitcnt lgkmcnt(8)
	v_mov_b32_e32 v64, v56
	ds_read_b128 v[104:107], v89 offset:13088
	s_waitcnt lgkmcnt(1)
	v_fma_f32 v6, v64, v6, v144
	v_fma_f32 v115, v100, v7, v6
	v_and_b32_e32 v7, 0xffff0000, v38
	v_and_b32_e32 v6, 0xffff0000, v34
	v_fma_f32 v6, v57, v6, v134
	v_fma_f32 v114, v101, v7, v6
	v_lshlrev_b32_e32 v7, 16, v39
	v_lshlrev_b32_e32 v6, 16, v35
	v_fma_f32 v6, v58, v6, v135
	v_fma_f32 v113, v102, v7, v6
	v_and_b32_e32 v7, 0xffff0000, v39
	v_and_b32_e32 v6, 0xffff0000, v35
	v_fma_f32 v6, v59, v6, v136
	v_fma_f32 v112, v103, v7, v6
	v_lshlrev_b32_e32 v7, 16, v40
	v_lshlrev_b32_e32 v6, 16, v36
	s_waitcnt lgkmcnt(0)
	v_fma_f32 v6, v60, v6, v122
	v_fma_f32 v111, v104, v7, v6
	v_and_b32_e32 v7, 0xffff0000, v40
	v_and_b32_e32 v6, 0xffff0000, v36
	v_fma_f32 v6, v61, v6, v123
	v_fma_f32 v110, v105, v7, v6
	v_lshlrev_b32_e32 v7, 16, v41
	v_lshlrev_b32_e32 v6, 16, v37
	v_fma_f32 v6, v62, v6, v108
	v_fma_f32 v109, v106, v7, v6
	v_and_b32_e32 v6, 0xffff0000, v37
	ds_read_b128 v[34:37], v89 offset:13120
	v_and_b32_e32 v7, 0xffff0000, v41
	v_fma_f32 v6, v63, v6, v124
	v_fma_f32 v100, v107, v7, v6
	v_lshlrev_b32_e32 v7, 16, v30
	v_lshlrev_b32_e32 v6, 16, v26
	ds_read_b128 v[38:41], v89 offset:13152
	s_waitcnt lgkmcnt(1)
	v_fma_f32 v6, v96, v6, v125
	v_fma_f32 v106, v34, v7, v6
	v_and_b32_e32 v7, 0xffff0000, v30
	v_and_b32_e32 v6, 0xffff0000, v26
	v_fma_f32 v6, v97, v6, v126
	v_fma_f32 v103, v35, v7, v6
	v_lshlrev_b32_e32 v7, 16, v31
	v_lshlrev_b32_e32 v6, 16, v27
	v_fma_f32 v6, v98, v6, v127
	v_fma_f32 v102, v36, v7, v6
	v_and_b32_e32 v7, 0xffff0000, v31
	v_and_b32_e32 v6, 0xffff0000, v27
	v_fma_f32 v6, v99, v6, v128
	v_fma_f32 v99, v37, v7, v6
	v_lshlrev_b32_e32 v7, 16, v32
	v_lshlrev_b32_e32 v6, 16, v28
	s_waitcnt lgkmcnt(0)
	v_fma_f32 v6, v118, v6, v129
	v_fma_f32 v97, v38, v7, v6
	v_and_b32_e32 v7, 0xffff0000, v32
	v_and_b32_e32 v6, 0xffff0000, v28
	v_fma_f32 v6, v119, v6, v130
	v_fma_f32 v96, v39, v7, v6
	v_lshlrev_b32_e32 v7, 16, v33
	v_lshlrev_b32_e32 v6, 16, v29
	v_fma_f32 v6, v120, v6, v131
	v_fma_f32 v95, v40, v7, v6
	v_and_b32_e32 v6, 0xffff0000, v29
	ds_read_b128 v[26:29], v89 offset:13184
	v_and_b32_e32 v7, 0xffff0000, v33
	v_fma_f32 v6, v121, v6, v117
	v_fma_f32 v90, v41, v7, v6
	v_lshlrev_b32_e32 v7, 16, v22
	v_lshlrev_b32_e32 v6, 16, v18
	ds_read_b128 v[30:33], v89 offset:13216
	s_waitcnt lgkmcnt(1)
	v_fma_f32 v6, v46, v6, v132
	v_fma_f32 v91, v26, v7, v6
	v_and_b32_e32 v7, 0xffff0000, v22
	v_and_b32_e32 v6, 0xffff0000, v18
	v_fma_f32 v6, v47, v6, v133
	v_fma_f32 v107, v27, v7, v6
	v_lshlrev_b32_e32 v7, 16, v23
	v_lshlrev_b32_e32 v6, 16, v19
	v_fma_f32 v6, v48, v6, v92
	v_fma_f32 v108, v28, v7, v6
	v_and_b32_e32 v7, 0xffff0000, v23
	v_and_b32_e32 v6, 0xffff0000, v19
	s_or_b32 s4, s4, s45
	v_fma_f32 v6, v49, v6, v54
	v_fma_f32 v105, v29, v7, v6
	s_lshl_b32 s4, s4, 3
	s_ashr_i32 s5, s48, 31
	s_add_u32 s4, s48, s4
	v_lshlrev_b32_e32 v7, 16, v24
	v_lshlrev_b32_e32 v6, 16, v20
	s_waitcnt lgkmcnt(0)
; __device__ __forceinline__ unsigned cvt_pk_bf16(float lo, float hi) { unsigned r; asm volatile("v_cvt_pk_bf16_f32 %0, %1, %2" : "=v"(r) : "v"(lo), "v"(hi)); return r; }
; #define GAS __attribute__((address_space(1)))
; #define LAS __attribute__((address_space(3)))
; template <int PASS>
; __device__ __forceinline__ void lru_unit(const LruPtrs& args, LAS unsigned char* lds, int chunk, int bl, int g, int ck) {
;     ...
;         for (int k = 0; k < 4; ++k) {
; #pragma unroll
;             for (int q = 0; q < 8; ++q) { const f32x4 cw = *(const LAS f32x4*)(PRM + k * 64 + 8 * q + 4 * hi);
;                 xc[q][0] += cw[0] * pg8::bf_lo(xw[k][q].x); xc[q][1] += cw[1] * pg8::bf_hi(xw[k][q].x); xc[q][2] += cw[2] * pg8::bf_lo(xw[k][q].y); xc[q][3] += cw[3] * pg8::bf_hi(xw[k][q].y); }
;         }
;         f32x16 ar[2], ai_[2];
; #pragma unroll
;         for (int rb = 0; rb < 2; ++rb) { ar[rb] = f32x16{}; ai_[rb] = f32x16{}; }
;         const GAS bf16* wrf = (const GAS bf16*)(ws + WS_WRF) + (size_t)g * (2 * 2 * 4 * 64 * 8) + lane * 8;
; #pragma unroll
;         for (int ks = 0; ks < 4; ++ks) {
;             v4u bw; bw.x = pg8::cvt_pk_bf16(xc[2 * ks][0], xc[2 * ks][1]); bw.y = pg8::cvt_pk_bf16(xc[2 * ks][2], xc[2 * ks][3]); bw.z = pg8::cvt_pk_bf16(xc[2 * ks + 1][0], xc[2 * ks + 1][1]); bw.w = pg8::cvt_pk_bf16(xc[2 * ks + 1][2], xc[2 * ks + 1][3]);
;             const bf16x8 bfr = __builtin_bit_cast(bf16x8, bw);
; #pragma unroll
;             for (int rb = 0; rb < 2; ++rb) {
;                 const bf16x8 wr_ = __builtin_bit_cast(bf16x8, *(const GAS v4u*)(wrf + ((0 * 2 + rb) * 4 + ks) * 512));
;                 const bf16x8 wi_ = __builtin_bit_cast(bf16x8, *(const GAS v4u*)(wrf + ((1 * 2 + rb) * 4 + ks) * 512));
;                 ar[rb] = __builtin_amdgcn_mfma_f32_32x32x16_bf16(wr_, bfr, ar[rb], 0, 0, 0);
;                 ai_[rb] = __builtin_amdgcn_mfma_f32_32x32x16_bf16(wi_, bfr, ai_[rb], 0, 0, 0);
;             }
;         }
	s_addc_u32 s5, s5, 0
	v_fma_f32 v6, v42, v6, v51
	v_fma_f32 v104, v30, v7, v6
	s_lshl_b64 s[4:5], s[4:5], 13
	s_add_u32 s4, s42, s4
	v_and_b32_e32 v7, 0xffff0000, v24
	v_and_b32_e32 v6, 0xffff0000, v20
	s_addc_u32 s5, s43, s5
	s_lshl_b32 s2, s2, 14
	v_fma_f32 v6, v43, v6, v52
	v_fma_f32 v101, v31, v7, v6
	s_add_u32 s48, s42, s2
	v_lshlrev_b32_e32 v0, 4, v86
	s_addc_u32 s49, s43, 0
	v_lshlrev_b32_e32 v7, 16, v25
	v_lshlrev_b32_e32 v6, 16, v21
	v_lshl_add_u64 v[38:39], s[48:49], 0, v[0:1]
	s_mov_b32 s2, 0x2501000
	v_fma_f32 v6, v44, v6, v50
	v_fma_f32 v98, v32, v7, v6
	v_add_co_u32_e32 v166, vcc, s2, v38
	s_nop 0
	v_addc_co_u32_e32 v167, vcc, 0, v39, vcc
	v_and_b32_e32 v7, 0xffff0000, v25
	v_and_b32_e32 v6, 0xffff0000, v21
	ds_read_b128 v[118:121], v89 offset:13248
	ds_read_b128 v[122:125], v89 offset:13280
	v_cvt_pk_bf16_f32 v126, v115, v114
	v_cvt_pk_bf16_f32 v127, v113, v112
	v_cvt_pk_bf16_f32 v128, v111, v110
	v_cvt_pk_bf16_f32 v129, v109, v100
	global_load_dwordx4 v[34:37], v[166:167], off offset:-4096
	global_load_dwordx4 v[130:133], v[166:167], off
	v_fma_f32 v6, v45, v6, v53
	v_fma_f32 v92, v33, v7, v6
	v_add_f32_e32 v117, v2, v3
	v_lshlrev_b32_e32 v3, 16, v8
	v_lshlrev_b32_e32 v2, 16, v4
	v_fma_f32 v2, v14, v2, v10
	v_fma_f32 v174, v74, v3, v2
	s_mov_b32 s2, 0x2503000
	v_and_b32_e32 v3, 0xffff0000, v8
	v_and_b32_e32 v2, 0xffff0000, v4
	v_mov_b32_e32 v74, v15
	v_add_co_u32_e32 v168, vcc, s2, v38
	v_pk_mul_f32 v[2:3], v[74:75], v[2:3]
	v_lshlrev_b32_e32 v19, 16, v70
	v_lshlrev_b32_e32 v18, 16, v66
	v_mov_b32_e32 v20, v82
	s_waitcnt lgkmcnt(1)
	v_mov_b32_e32 v21, v118
	v_addc_co_u32_e32 v169, vcc, 0, v39, vcc
	v_add_f32_e32 v2, v11, v2
	v_pk_mul_f32 v[18:19], v[20:21], v[18:19]
	global_load_dwordx4 v[56:59], v[168:169], off offset:-4096
	global_load_dwordx4 v[26:29], v[168:169], off
	v_cvt_pk_bf16_f32 v134, v106, v103
	v_cvt_pk_bf16_f32 v135, v102, v99
	v_cvt_pk_bf16_f32 v136, v97, v96
	v_cvt_pk_bf16_f32 v137, v95, v90
	global_load_dwordx4 v[146:149], v[166:167], off offset:1024
	global_load_dwordx4 v[150:153], v[168:169], off offset:1024
	v_add_f32_e32 v175, v2, v3
	v_lshlrev_b32_e32 v3, 16, v9
	v_lshlrev_b32_e32 v2, 16, v5
	v_add_f32_e32 v18, v94, v18
	v_fma_f32 v2, v16, v2, v12
	v_fma_f32 v176, v76, v3, v2
	v_add_f32_e32 v94, v18, v19
	v_and_b32_e32 v19, 0xffff0000, v70
	v_and_b32_e32 v18, 0xffff0000, v66
	v_mov_b32_e32 v118, v83
	v_pk_mul_f32 v[74:75], v[118:119], v[18:19]
	v_and_b32_e32 v3, 0xffff0000, v9
	v_and_b32_e32 v2, 0xffff0000, v5
	v_mov_b32_e32 v76, v17
	v_add_f32_e32 v66, v93, v74
	v_pk_mul_f32 v[2:3], v[76:77], v[2:3]
	v_add_f32_e32 v93, v66, v75
	v_lshlrev_b32_e32 v75, 16, v71
	v_lshlrev_b32_e32 v74, 16, v67
	s_mov_b32 s2, 0x2502000
	v_fma_f32 v66, v84, v74, v116
	v_fma_f32 v83, v120, v75, v66
	s_mov_b64 s[48:49], 0x2500000
	v_add_co_u32_e32 v172, vcc, s2, v38
	v_and_b32_e32 v71, 0xffff0000, v71
	v_and_b32_e32 v70, 0xffff0000, v67
	v_lshl_add_u64 v[170:171], v[38:39], 0, s[48:49]
	v_addc_co_u32_e32 v173, vcc, 0, v39, vcc
	v_fma_f32 v66, v85, v70, v117
	v_fma_f32 v82, v121, v71, v66
	global_load_dwordx4 v[138:141], v[170:171], off offset:1024
	global_load_dwordx4 v[142:145], v[172:173], off offset:1024
	v_cvt_pk_bf16_f32 v154, v91, v107
	v_cvt_pk_bf16_f32 v155, v108, v105
	v_cvt_pk_bf16_f32 v156, v104, v101
	v_cvt_pk_bf16_f32 v157, v98, v92
	global_load_dwordx4 v[116:119], v[166:167], off offset:2048
	v_lshlrev_b32_e32 v67, 16, v72
	v_lshlrev_b32_e32 v66, 16, v68
	s_waitcnt lgkmcnt(0)
	v_fma_f32 v66, v78, v66, v174
	v_fma_f32 v77, v122, v67, v66
	v_and_b32_e32 v67, 0xffff0000, v72
	v_and_b32_e32 v66, 0xffff0000, v68
	v_fma_f32 v66, v79, v66, v175
	v_fma_f32 v76, v123, v67, v66
	global_load_dwordx4 v[120:123], v[168:169], off offset:2048
	global_load_dwordx4 v[158:161], v[170:171], off offset:2048
	global_load_dwordx4 v[162:165], v[172:173], off offset:2048
	v_lshlrev_b32_e32 v67, 16, v73
	v_lshlrev_b32_e32 v66, 16, v69
	v_fma_f32 v66, v80, v66, v176
	v_fma_f32 v74, v124, v67, v66
	v_add_f32_e32 v2, v13, v2
	v_and_b32_e32 v67, 0xffff0000, v73
	v_and_b32_e32 v66, 0xffff0000, v69
	v_mov_b32_e32 v124, v81
	v_add_f32_e32 v177, v2, v3
	s_waitcnt vmcnt(10)
	v_mfma_f32_32x32x16_bf16 v[2:17], v[130:133], v[126:129], 0
	v_mul_f32_e64 v66, v124, v66
	v_mul_f32_e64 v67, v125, v67
	v_cvt_pk_bf16_f32 v78, v94, v93
	v_cvt_pk_bf16_f32 v79, v83, v82
	v_cvt_pk_bf16_f32 v80, v77, v76
	s_mov_b32 s2, 0x29c01000
	v_add_f32_e32 v66, v177, v66
	v_add_f32_e32 v75, v66, v67
	v_cvt_pk_bf16_f32 v81, v74, v75
	global_load_dwordx4 v[66:69], v[170:171], off offset:3072
	global_load_dwordx4 v[70:73], v[172:173], off offset:3072
	s_waitcnt vmcnt(9)
	v_mfma_f32_32x32x16_bf16 v[2:17], v[146:149], v[134:137], v[2:17]
	s_waitcnt vmcnt(5)
	v_mfma_f32_32x32x16_bf16 v[2:17], v[116:119], v[154:157], v[2:17]
	global_load_dwordx4 v[116:119], v[166:167], off offset:3072
	v_mfma_f32_32x32x16_bf16 v[18:33], v[26:29], v[126:129], 0
	v_mfma_f32_32x32x16_bf16 v[34:49], v[34:37], v[126:129], 0
	v_mfma_f32_32x32x16_bf16 v[18:33], v[150:153], v[134:137], v[18:33]
	v_mfma_f32_32x32x16_bf16 v[50:65], v[56:59], v[126:129], 0
	ds_read_b128 v[124:127], v89 offset:13568
	ds_read_b128 v[128:131], v89 offset:13600
	v_mfma_f32_32x32x16_bf16 v[34:49], v[138:141], v[134:137], v[34:49]
	s_waitcnt vmcnt(5)
; __device__ __forceinline__ unsigned cvt_pk_bf16(float lo, float hi) { unsigned r; asm volatile("v_cvt_pk_bf16_f32 %0, %1, %2" : "=v"(r) : "v"(lo), "v"(hi)); return r; }
; __device__ __forceinline__ float sigm(float x) { return __builtin_amdgcn_rcpf(1.f + __expf(-x)); }
; #define GAS __attribute__((address_space(1)))
; #define LAS __attribute__((address_space(3)))
; template <int PASS>
; __device__ __forceinline__ void lru_unit(const LruPtrs& args, LAS unsigned char* lds, int chunk, int bl, int g, int ck) {
;     ...
;         for (int ks = 0; ks < 4; ++ks) {
;             v4u bw; bw.x = pg8::cvt_pk_bf16(xc[2 * ks][0], xc[2 * ks][1]); bw.y = pg8::cvt_pk_bf16(xc[2 * ks][2], xc[2 * ks][3]); bw.z = pg8::cvt_pk_bf16(xc[2 * ks + 1][0], xc[2 * ks + 1][1]); bw.w = pg8::cvt_pk_bf16(xc[2 * ks + 1][2], xc[2 * ks + 1][3]);
;             const bf16x8 bfr = __builtin_bit_cast(bf16x8, bw);
; #pragma unroll
;             for (int rb = 0; rb < 2; ++rb) {
;                 const bf16x8 wr_ = __builtin_bit_cast(bf16x8, *(const GAS v4u*)(wrf + ((0 * 2 + rb) * 4 + ks) * 512));
;                 const bf16x8 wi_ = __builtin_bit_cast(bf16x8, *(const GAS v4u*)(wrf + ((1 * 2 + rb) * 4 + ks) * 512));
;                 ar[rb] = __builtin_amdgcn_mfma_f32_32x32x16_bf16(wr_, bfr, ar[rb], 0, 0, 0);
;                 ai_[rb] = __builtin_amdgcn_mfma_f32_32x32x16_bf16(wi_, bfr, ai_[rb], 0, 0, 0);
;             }
;         }
; #pragma unroll
;         for (int q = 0; q < 8; ++q) {
;             const f32x4 br = *(const LAS f32x4*)(PRM + 5 * 64 + 8 * q + 4 * hi), bi = *(const LAS f32x4*)(PRM + 6 * 64 + 8 * q + 4 * hi), cf = *(const LAS f32x4*)(PRM + 7 * 64 + 8 * q + 4 * hi);
; #pragma unroll
;             for (int p = 0; p < 4; ++p) { const int rb = q >> 2, r = (q & 3) * 4 + p;
;                 const float rr = pg8::sigm(ar[rb][r] + br[p]), ii = pg8::sigm(ai_[rb][r] + bi[p]);
;                 const float a0 = __builtin_amdgcn_exp2f(cf[p] * rr);
;                 av[q][p] = a0; uv[q][p] = __builtin_amdgcn_sqrtf(fmaxf(1.f - a0 * a0, 0.f)) * (ii * xc[q][p]); }
	v_mfma_f32_32x32x16_bf16 v[18:33], v[120:123], v[154:157], v[18:33]
	global_load_dwordx4 v[120:123], v[168:169], off offset:3072
	v_mfma_f32_32x32x16_bf16 v[50:65], v[142:145], v[134:137], v[50:65]
	s_waitcnt vmcnt(5)
	v_mfma_f32_32x32x16_bf16 v[34:49], v[158:161], v[154:157], v[34:49]
	s_waitcnt vmcnt(4)
	v_mfma_f32_32x32x16_bf16 v[50:65], v[162:165], v[154:157], v[50:65]
	s_waitcnt vmcnt(3)
	v_mfma_f32_32x32x16_bf16 v[34:49], v[66:69], v[78:81], v[34:49]
	s_waitcnt vmcnt(2)
	v_mfma_f32_32x32x16_bf16 v[50:65], v[70:73], v[78:81], v[50:65]
	v_lshl_add_u64 v[72:73], s[4:5], 0, v[0:1]
	s_waitcnt lgkmcnt(1)
	s_nop 7
	v_add_f32_e32 v0, v34, v124
	v_mul_f32_e32 v0, 0xbfb8aa3b, v0
	v_exp_f32_e32 v0, v0
	v_add_f32_e32 v35, v35, v125
	v_mul_f32_e32 v35, 0xbfb8aa3b, v35
	v_exp_f32_e32 v35, v35
	s_waitcnt vmcnt(1)
	v_mfma_f32_32x32x16_bf16 v[2:17], v[116:119], v[78:81], v[2:17]
	ds_read_b128 v[116:119], v89 offset:13824
	ds_read_b128 v[132:135], v89 offset:14080
	v_add_f32_e32 v0, 1.0, v0
	v_rcp_f32_e32 v0, v0
	v_add_f32_e32 v35, 1.0, v35
	s_waitcnt lgkmcnt(1)
	v_add_f32_e32 v34, v50, v116
	v_mul_f32_e32 v34, 0xbfb8aa3b, v34
	s_waitcnt lgkmcnt(0)
	v_mul_f32_e32 v0, v132, v0
	v_exp_f32_e32 v34, v34
	v_exp_f32_e32 v66, v0
	v_rcp_f32_e32 v35, v35
	v_add_f32_e32 v50, v51, v117
	v_add_f32_e32 v0, 1.0, v34
	v_fma_f32 v34, -v66, v66, 1.0
	v_rcp_f32_e32 v0, v0
	v_max_f32_e32 v34, 0, v34
	v_mul_f32_e32 v50, 0xbfb8aa3b, v50
	v_mul_f32_e32 v35, v133, v35
	v_sqrt_f32_e32 v34, v34
	v_exp_f32_e32 v50, v50
	v_exp_f32_e32 v68, v35
	v_mul_f32_e32 v0, v115, v0
	v_mul_f32_e32 v67, v0, v34
	v_add_f32_e32 v0, 1.0, v50
	v_fma_f32 v34, -v68, v68, 1.0
	v_add_f32_e32 v35, v36, v126
	v_rcp_f32_e32 v0, v0
	v_mul_f32_e32 v35, 0xbfb8aa3b, v35
	v_max_f32_e32 v34, 0, v34
	v_exp_f32_e32 v35, v35
	v_sqrt_f32_e32 v36, v34
	v_mul_f32_e32 v0, v114, v0
	v_add_f32_e32 v38, v38, v128
	v_add_f32_e32 v34, 1.0, v35
	v_mul_f32_e32 v69, v0, v36
	v_add_f32_e32 v36, v37, v127
	v_rcp_f32_e32 v34, v34
	v_mul_f32_e32 v36, 0xbfb8aa3b, v36
	v_exp_f32_e32 v36, v36
	v_add_f32_e32 v35, v52, v118
	v_mul_f32_e32 v35, 0xbfb8aa3b, v35
	v_mul_f32_e32 v34, v134, v34
	v_exp_f32_e32 v35, v35
	v_exp_f32_e32 v34, v34
	v_add_f32_e32 v36, 1.0, v36
	v_rcp_f32_e32 v36, v36
	v_mul_f32_e32 v38, 0xbfb8aa3b, v38
	v_exp_f32_e32 v38, v38
	v_add_f32_e32 v0, 1.0, v35
	v_fma_f32 v35, -v34, v34, 1.0
	v_add_f32_e32 v37, v53, v119
	ds_read_b128 v[136:139], v89 offset:13856
	ds_read_b128 v[140:143], v89 offset:14112
	v_rcp_f32_e32 v0, v0
	v_max_f32_e32 v35, 0, v35
	v_mul_f32_e32 v37, 0xbfb8aa3b, v37
	v_mul_f32_e32 v36, v135, v36
	v_sqrt_f32_e32 v35, v35
	v_exp_f32_e32 v37, v37
	v_exp_f32_e32 v36, v36
	v_add_f32_e32 v38, 1.0, v38
	v_add_f32_e32 v39, v39, v129
	v_rcp_f32_e32 v38, v38
	v_mul_f32_e32 v39, 0xbfb8aa3b, v39
	v_exp_f32_e32 v39, v39
	v_mul_f32_e32 v0, v113, v0
	v_mul_f32_e32 v35, v0, v35
	v_add_f32_e32 v0, 1.0, v37
	v_fma_f32 v37, -v36, v36, 1.0
	s_waitcnt lgkmcnt(1)
	v_add_f32_e32 v50, v54, v136
	v_rcp_f32_e32 v0, v0
	v_max_f32_e32 v37, 0, v37
	v_mul_f32_e32 v50, 0xbfb8aa3b, v50
	s_waitcnt lgkmcnt(0)
	v_mul_f32_e32 v38, v140, v38
	v_sqrt_f32_e32 v37, v37
	v_exp_f32_e32 v51, v50
	v_exp_f32_e32 v50, v38
	v_add_f32_e32 v39, 1.0, v39
	v_rcp_f32_e32 v39, v39
	v_mul_f32_e32 v0, v112, v0
	v_mul_f32_e32 v37, v0, v37
	v_add_f32_e32 v0, 1.0, v51
	v_fma_f32 v38, -v50, v50, 1.0
	v_rcp_f32_e32 v0, v0
	v_max_f32_e32 v38, 0, v38
	v_add_f32_e32 v51, v55, v137
	v_mul_f32_e32 v39, v141, v39
	v_sqrt_f32_e32 v38, v38
	v_mul_f32_e32 v51, 0xbfb8aa3b, v51
	v_exp_f32_e32 v52, v39
	v_add_f32_e32 v39, v40, v130
	v_exp_f32_e32 v53, v51
	v_mul_f32_e32 v39, 0xbfb8aa3b, v39
	v_exp_f32_e32 v39, v39
	v_mul_f32_e32 v0, v111, v0
	v_mul_f32_e32 v51, v0, v38
	v_fma_f32 v38, -v52, v52, 1.0
	v_add_f32_e32 v0, 1.0, v53
	v_max_f32_e32 v38, 0, v38
	v_rcp_f32_e32 v0, v0
	v_sqrt_f32_e32 v40, v38
	v_add_f32_e32 v38, 1.0, v39
	v_rcp_f32_e32 v38, v38
	v_mul_f32_e32 v0, v110, v0
	v_add_f32_e32 v39, v56, v138
	v_mul_f32_e32 v39, 0xbfb8aa3b, v39
	v_mul_f32_e32 v38, v142, v38
	v_mul_f32_e32 v53, v0, v40
	v_add_f32_e32 v40, v41, v131
	s_waitcnt vmcnt(0)
	v_mfma_f32_32x32x16_bf16 v[18:33], v[120:123], v[78:81], v[18:33]
	v_exp_f32_e32 v39, v39
	v_exp_f32_e32 v38, v38
	v_mul_f32_e32 v40, 0xbfb8aa3b, v40
	ds_read_b128 v[78:81], v89 offset:13632
	ds_read_b128 v[110:113], v89 offset:13664
	v_mov_b32_e32 v180, s86
	ds_read_b32 v180, v180 offset:64
	s_waitcnt lgkmcnt(0)
	v_readfirstlane_b32 s98, v180
	s_sub_i32 s98, s98, s100
	s_cmp_ge_u32 s98, 0x400
	s_cbranch_scc1 .Llpf_skip
	s_lshr_b32 s4, s98, 9
	s_lshl_b32 s4, s4, 13
	v_bfe_u32 v181, v236, 3, 3
	v_and_b32_e32 v182, 0x1c0, v236
	v_lshrrev_b32_e32 v182, 1, v182
	v_add3_u32 v181, v181, v182, s4
	s_and_b32 s4, s98, 31
	s_lshl_b32 s4, s4, 8
	v_add_u32_e32 v181, s4, v181
	v_add_u32_e32 v181, -3, v181
	v_max_i32_e32 v181, 0, v181
	s_bfe_u32 s4, s98, 0x40005
	s_lshl_b32 s4, s4, 7
	v_and_b32_e32 v182, 7, v236
	v_lshlrev_b32_e32 v182, 4, v182
	v_add_u32_e32 v182, s4, v182
	v_lshl_add_u32 v181, v181, 11, v182
	s_add_u32 s4, s40, 0x13c00000
	s_addc_u32 s5, s41, 0
	v_add_u32_e32 v183, 0x4000, v181
	v_add_u32_e32 v184, 0x8000, v181
	v_add_u32_e32 v185, 0xc000, v181
	global_load_dwordx4 v[188:191], v181, s[4:5]
	global_load_dwordx4 v[192:195], v183, s[4:5]
	global_load_dwordx4 v[196:199], v184, s[4:5]
	global_load_dwordx4 v[200:203], v185, s[4:5]
